# phase order split by XCD parity (bit 0 of workgroup id) instead of bit 3: whole XCDs run the HGRN/S5 output passes first
# speedup vs baseline: 1.0209x; 1.0055x over previous
.Lord_att:
	s_mov_b64 s[10:11], s[84:85]
	s_waitcnt lgkmcnt(0)
	v_mov_b32_e32 v0, v173
	s_barrier
	s_getreg_b32 s1, hwreg(HW_REG_HW_ID, 0, 7)
	s_and_b32 s1, s1, 63
	s_lshl_b32 s1, s1, 2
	v_mov_b32_e32 v1, s1
	ds_read_b32 v6, v1
	s_load_dwordx8 s[12:19], s[10:11], 0x90
	v_and_b32_e32 v1, 63, v0
	s_lshl_b32 s66, s70, 6
	v_or_b32_e32 v160, s66, v1
	v_lshlrev_b64 v[2:3], 2, v[160:161]
	s_waitcnt lgkmcnt(0)
	v_lshl_add_u64 v[4:5], s[12:13], 0, v[2:3]
	global_load_dword v7, v[4:5], off
	v_lshl_add_u64 v[4:5], s[14:15], 0, v[2:3]
	global_load_dword v8, v[4:5], off
	v_lshl_add_u64 v[4:5], s[16:17], 0, v[2:3]
	v_lshl_add_u64 v[2:3], s[18:19], 0, v[2:3]
	global_load_dword v4, v[4:5], off
	v_readfirstlane_b32 s1, v6
	global_load_dword v2, v[2:3], off
	s_load_dwordx2 s[12:13], s[10:11], 0xb0
	s_getreg_b32 s6, hwreg(HW_REG_HW_ID, 0, 7)
	s_and_b32 s6, s6, 63
	s_lshl_b32 s6, s6, 2
	s_lshl_b32 s1, s1, 6
	s_and_b32 s1, s1, 0x3fc0
	s_waitcnt vmcnt(2)
	v_mul_f32_e32 v3, v7, v8
	ds_bpermute_b32 v3, v176, v3
	s_waitcnt vmcnt(0)
	v_mul_f32_e32 v5, v4, v2
	ds_bpermute_b32 v5, v176, v5
	s_waitcnt lgkmcnt(0)
	v_fmac_f32_e32 v3, v7, v8
	v_mov_b32_e32 v7, s6
	v_readlane_b32 s6, v255, 12
	v_readlane_b32 s7, v255, 13
	v_fmac_f32_e32 v5, v4, v2
	ds_bpermute_b32 v2, v177, v3
	ds_bpermute_b32 v4, v177, v5
	s_and_b64 vcc, exec, s[6:7]
	s_waitcnt lgkmcnt(1)
	v_add_f32_e32 v2, v3, v2
	s_waitcnt lgkmcnt(0)
	v_add_f32_e32 v3, v5, v4
	ds_bpermute_b32 v4, v178, v2
	ds_bpermute_b32 v5, v178, v3
	s_waitcnt lgkmcnt(1)
	v_add_f32_e32 v2, v2, v4
	s_waitcnt lgkmcnt(0)
	v_add_f32_e32 v3, v3, v5
	ds_bpermute_b32 v4, v179, v2
	ds_bpermute_b32 v5, v179, v3
	s_waitcnt lgkmcnt(1)
	v_add_f32_e32 v2, v2, v4
	s_waitcnt lgkmcnt(0)
	v_add_f32_e32 v3, v3, v5
	ds_bpermute_b32 v4, v180, v2
	ds_bpermute_b32 v6, v180, v3
	s_waitcnt lgkmcnt(1)
	v_add_f32_e32 v5, v2, v4
	s_waitcnt lgkmcnt(0)
	v_add_f32_e32 v3, v3, v6
	ds_bpermute_b32 v6, v181, v5
	ds_bpermute_b32 v4, v181, v3
	ds_read_b32 v2, v7
	s_waitcnt lgkmcnt(0)
	v_add_u32_e32 v2, s1, v0
	s_nop 0
	v_readfirstlane_b32 s1, v2
	s_cbranch_vccnz .LBB0_423
	s_cmp_eq_u32 s100, 1
	s_cbranch_scc1 .Lord_go
	s_bitcmp1_b32 s2, 0
	s_cbranch_scc0 .Lord_go
	s_mov_b32 s100, 2
	s_branch .LBB0_423
